# GEMM phase prologues: K-tile 1 LDS-DMA loads issued before the first wait/barrier (one cold latency instead of two)
# baseline (speedup 1.0000x reference)
; #define PG8_STAGE(bufoff, gbase, voff) do { _Pragma("unroll") for (int _i = 0; _i < 2; ++_i) \
;         __builtin_amdgcn_global_load_lds((const unsigned*)((const char*)(gbase) + (voff)[_i]), (PG8_LAS unsigned*)(lds + (bufoff) + ldsw + _i * 8192), 16, 0, 0); } while (0)
; #define PG8_WAIT_V(n) asm volatile("s_waitcnt vmcnt(" #n ")" ::: "memory")
; #define PG8_BAR __builtin_amdgcn_s_barrier()
; template <class Epi, class Sched, bool ALIGN_EPI = false, bool SP2 = false, bool MID = false>
; __device__ __forceinline__ void gemm_phase(PG8_LAS unsigned char* lds, const Gemm g, const Sched& S, const Epi& E, const PG8_LAS float* mid = nullptr) {
;     ...
;     for (int i = 0; i < 2; ++i) { int R, C; stage_rc(tid * 16 + i * 8192, R, C); const int Rb = Epi::PERM ? ((R & ~31) + perm32(R & 31)) : R;
;         voffA[i] = (unsigned)(R * g.lda + C) * 2u; voffB[i] = (unsigned)(Rb * g.ldb + C) * 2u; }
;     const size_t kstep = (size_t)(BK * 2);
;     const size_t hstepA = (size_t)HALF * g.lda * 2, hstepB = (size_t)HALF * g.ldb * 2;
;     const size_t tstepA = 2 * hstepA, tstepB = 2 * hstepB;
;     const unsigned ldsw = (unsigned)wid * 1024u;
;     const int aoff = lds_byte(wr * 64 + fr, fq * 8), boff = lds_byte(wc * 32 + fr, fq * 8);
;     ...
;         PG8_STAGE(PG8_SB(0, 0), cB, voffB); PG8_STAGE(PG8_SB(0, 1), cB + hstepB, voffB); PG8_STAGE(PG8_SA(0, 0), cA, voffA); PG8_STAGE(PG8_SA(0, 1), cA + hstepA, voffA);
;         if (wr == 1) PG8_BAR;
;         PG8_WAIT_V(2); PG8_BAR;
;         PG8_STAGE(PG8_SB(1, 0), cB + kstep, voffB); PG8_STAGE(PG8_SA(1, 0), cA + kstep, voffA); PG8_STAGE(PG8_SB(1, 1), cB + hstepB + kstep, voffB);
;         PG8_WAIT_V(6); PG8_BAR;
.LBB0_186:
	v_lshrrev_b32_e32 v16, 1, v14
	v_and_b32_e32 v16, 24, v16
	s_add_u32 s14, s14, 0x7400000
	v_and_b32_e32 v15, 15, v14
	v_lshlrev_b32_e32 v17, 1, v16
	v_lshlrev_b32_e32 v14, 2, v14
	s_sext_i32_i8 s60, s10
	s_addc_u32 s15, s15, 0
	v_lshl_or_b32 v141, s21, 6, v15
	v_lshl_or_b32 v15, v15, 6, v17
	s_lshl_b32 s10, s21, 13
	v_and_b32_e32 v14, 32, v14
	v_bitop3_b32 v17, v15, s10, v14 bitop3:0xde
	s_lshl_b32 s10, s20, 5
	s_and_b32 s36, s10, 0x60
	s_lshl_b32 s10, s36, 7
	s_add_i32 m0, s43, 0x18000
	v_lshl_add_u64 v[6:7], v[6:7], 0, s[16:17]
	v_bitop3_b32 v146, v15, s10, v14 bitop3:0xde
	global_load_lds_dwordx4 v[6:7], off
	v_lshl_add_u64 v[4:5], v[4:5], 0, s[16:17]
	s_add_i32 m0, s43, 0x1a000
	s_add_i32 s10, s43, 0x8000
	s_add_i32 s57, s43, 0xa000
	global_load_lds_dwordx4 v[4:5], off
	v_lshl_add_u64 v[0:1], v[0:1], 0, s[16:17]
	s_mov_b32 m0, s10
	s_add_u32 s20, s48, 0x40080
	global_load_lds_dwordx4 v[0:1], off
	v_lshl_add_u64 v[0:1], v[2:3], 0, s[16:17]
	s_mov_b32 m0, s57
	s_addc_u32 s21, s49, 0
	global_load_lds_dwordx4 v[0:1], off
	s_add_i32 m0, s43, 0x1c000
	v_lshl_add_u64 v[0:1], s[20:21], 0, v[80:81]
	global_load_lds_dwordx4 v[0:1], off
	v_lshl_add_u64 v[0:1], s[20:21], 0, v[130:131]
	s_add_i32 m0, s43, 0x1e000
	s_cmpk_lt_u32 s3, 0x100
	global_load_lds_dwordx4 v[0:1], off
	v_lshlrev_b32_e32 v0, 14, v12
	v_and_b32_e32 v0, 0xffff8000, v0
	v_lshl_add_u32 v0, v11, 11, v0
	v_and_b32_e32 v1, 1, v12
	v_lshl_or_b32 v0, v1, 6, v0
	v_lshl_add_u32 v136, v13, 1, v0
	v_lshlrev_b32_e32 v0, 14, v8
	v_and_b32_e32 v0, 0xffff8000, v0
	s_waitcnt vmcnt(8)
	s_barrier
	s_waitcnt vmcnt(6)
	v_lshl_add_u32 v0, v9, 11, v0
	v_and_b32_e32 v1, 1, v8
	v_lshl_or_b32 v0, v1, 6, v0
	s_cselect_b64 s[20:21], -1, 0
	s_ashr_i32 s58, s2, 31
	v_or_b32_e32 v147, s36, v16
	v_mov_b32_e32 v137, v81
	v_lshl_add_u32 v138, v10, 1, v0
	v_mov_b32_e32 v139, v81
	s_mov_b32 s59, 0
	v_add_u32_e32 v148, 0, v17
	s_barrier
	s_branch .LBB0_189

; #define PG8_STAGE(bufoff, gbase, voff) do { _Pragma("unroll") for (int _i = 0; _i < 2; ++_i) \
;         __builtin_amdgcn_global_load_lds((const unsigned*)((const char*)(gbase) + (voff)[_i]), (PG8_LAS unsigned*)(lds + (bufoff) + ldsw + _i * 8192), 16, 0, 0); } while (0)
; #define PG8_WAIT_V(n) asm volatile("s_waitcnt vmcnt(" #n ")" ::: "memory")
; #define PG8_BAR __builtin_amdgcn_s_barrier()
; template <class Epi, class Sched, bool ALIGN_EPI = false, bool SP2 = false, bool MID = false>
; __device__ __forceinline__ void gemm_phase(PG8_LAS unsigned char* lds, const Gemm g, const Sched& S, const Epi& E, const PG8_LAS float* mid = nullptr) {
;     ...
;     for (int i = 0; i < 2; ++i) { int R, C; stage_rc(tid * 16 + i * 8192, R, C); const int Rb = Epi::PERM ? ((R & ~31) + perm32(R & 31)) : R;
;         voffA[i] = (unsigned)(R * g.lda + C) * 2u; voffB[i] = (unsigned)(Rb * g.ldb + C) * 2u; }
;     const size_t kstep = (size_t)(BK * 2);
;     const size_t hstepA = (size_t)HALF * g.lda * 2, hstepB = (size_t)HALF * g.ldb * 2;
;     const size_t tstepA = 2 * hstepA, tstepB = 2 * hstepB;
;     const unsigned ldsw = (unsigned)wid * 1024u;
;     const int aoff = lds_byte(wr * 64 + fr, fq * 8), boff = lds_byte(wc * 32 + fr, fq * 8);
;     ...
;         PG8_STAGE(PG8_SB(0, 0), cB, voffB); PG8_STAGE(PG8_SB(0, 1), cB + hstepB, voffB); PG8_STAGE(PG8_SA(0, 0), cA, voffA); PG8_STAGE(PG8_SA(0, 1), cA + hstepA, voffA);
;         if (wr == 1) PG8_BAR;
;         PG8_WAIT_V(2); PG8_BAR;
;         PG8_STAGE(PG8_SB(1, 0), cB + kstep, voffB); PG8_STAGE(PG8_SA(1, 0), cA + kstep, voffA); PG8_STAGE(PG8_SB(1, 1), cB + hstepB + kstep, voffB);
;         PG8_WAIT_V(6); PG8_BAR;
.LBB0_402:
	v_lshrrev_b32_e32 v16, 1, v14
	v_and_b32_e32 v16, 24, v16
	v_and_b32_e32 v15, 15, v14
	v_lshlrev_b32_e32 v17, 1, v16
	v_lshlrev_b32_e32 v14, 2, v14
	s_sext_i32_i8 s5, s10
	v_lshl_or_b32 v198, s20, 6, v15
	v_lshl_or_b32 v15, v15, 6, v17
	s_lshl_b32 s10, s20, 13
	v_and_b32_e32 v14, 32, v14
	v_bitop3_b32 v17, v15, s10, v14 bitop3:0xde
	s_lshl_b32 s10, s21, 5
	s_and_b32 s36, s10, 0x60
	s_lshl_b32 s10, s36, 7
	s_add_i32 m0, s19, 0x18000
	v_lshl_add_u64 v[6:7], v[6:7], 0, s[16:17]
	v_bitop3_b32 v199, v15, s10, v14 bitop3:0xde
	global_load_lds_dwordx4 v[6:7], off
	v_lshl_add_u64 v[4:5], v[4:5], 0, s[16:17]
	s_add_i32 m0, s19, 0x1a000
	s_add_i32 s10, s19, 0x8000
	s_add_i32 s69, s19, 0xa000
	global_load_lds_dwordx4 v[4:5], off
	v_lshl_add_u64 v[0:1], v[0:1], 0, s[16:17]
	s_mov_b32 m0, s10
	s_add_u32 s20, s12, 0x40080
	global_load_lds_dwordx4 v[0:1], off
	v_lshl_add_u64 v[0:1], v[2:3], 0, s[16:17]
	s_mov_b32 m0, s69
	s_addc_u32 s21, s13, 0
	global_load_lds_dwordx4 v[0:1], off
	s_add_i32 m0, s19, 0x1c000
	v_lshl_add_u64 v[0:1], s[20:21], 0, v[150:151]
	global_load_lds_dwordx4 v[0:1], off
	v_lshl_add_u64 v[0:1], s[20:21], 0, v[154:155]
	s_add_i32 m0, s19, 0x1e000
	s_cmpk_lt_u32 s3, 0x100
	global_load_lds_dwordx4 v[0:1], off
	v_lshlrev_b32_e32 v0, 14, v11
	v_and_b32_e32 v0, 0xffff8000, v0
	v_lshl_add_u32 v0, v12, 11, v0
	v_and_b32_e32 v1, 1, v11
	v_lshl_or_b32 v0, v1, 6, v0
	v_lshl_add_u32 v156, v13, 1, v0
	v_lshlrev_b32_e32 v0, 14, v8
	v_and_b32_e32 v0, 0xffff8000, v0
	s_waitcnt vmcnt(8)
	s_barrier
	s_waitcnt vmcnt(6)
	v_lshl_add_u32 v0, v9, 11, v0
	v_and_b32_e32 v1, 1, v8
	v_lshl_or_b32 v0, v1, 6, v0
	s_cselect_b64 s[44:45], -1, 0
	v_or_b32_e32 v200, 16, v198
	v_or_b32_e32 v201, 32, v198
	v_or_b32_e32 v202, 48, v198
	v_or_b32_e32 v203, s36, v16
	v_mov_b32_e32 v157, v81
	v_lshl_add_u32 v158, v10, 1, v0
	v_mov_b32_e32 v159, v81
	s_mov_b32 s3, 0
	v_add_u32_e32 v204, 0, v17
	s_barrier
	s_branch .LBB0_405

; #define PG8_STAGE(bufoff, gbase, voff) do { _Pragma("unroll") for (int _i = 0; _i < 2; ++_i) \
;         __builtin_amdgcn_global_load_lds((const unsigned*)((const char*)(gbase) + (voff)[_i]), (PG8_LAS unsigned*)(lds + (bufoff) + ldsw + _i * 8192), 16, 0, 0); } while (0)
; #define PG8_WAIT_V(n) asm volatile("s_waitcnt vmcnt(" #n ")" ::: "memory")
; #define PG8_BAR __builtin_amdgcn_s_barrier()
; template <class Epi, class Sched, bool ALIGN_EPI = false, bool SP2 = false, bool MID = false>
; __device__ __forceinline__ void gemm_phase(PG8_LAS unsigned char* lds, const Gemm g, const Sched& S, const Epi& E, const PG8_LAS float* mid = nullptr) {
;     ...
;     for (int i = 0; i < 2; ++i) { int R, C; stage_rc(tid * 16 + i * 8192, R, C); const int Rb = Epi::PERM ? ((R & ~31) + perm32(R & 31)) : R;
;         voffA[i] = (unsigned)(R * g.lda + C) * 2u; voffB[i] = (unsigned)(Rb * g.ldb + C) * 2u; }
;     const size_t kstep = (size_t)(BK * 2);
;     const size_t hstepA = (size_t)HALF * g.lda * 2, hstepB = (size_t)HALF * g.ldb * 2;
;     const size_t tstepA = 2 * hstepA, tstepB = 2 * hstepB;
;     const unsigned ldsw = (unsigned)wid * 1024u;
;     const int aoff = lds_byte(wr * 64 + fr, fq * 8), boff = lds_byte(wc * 32 + fr, fq * 8);
;     ...
;         PG8_STAGE(PG8_SB(0, 0), cB, voffB); PG8_STAGE(PG8_SB(0, 1), cB + hstepB, voffB); PG8_STAGE(PG8_SA(0, 0), cA, voffA); PG8_STAGE(PG8_SA(0, 1), cA + hstepA, voffA);
;         if (wr == 1) PG8_BAR;
;         PG8_WAIT_V(2); PG8_BAR;
;         PG8_STAGE(PG8_SB(1, 0), cB + kstep, voffB); PG8_STAGE(PG8_SA(1, 0), cA + kstep, voffA); PG8_STAGE(PG8_SB(1, 1), cB + hstepB + kstep, voffB);
;         PG8_WAIT_V(6); PG8_BAR;
.LBB0_430:
	v_lshrrev_b32_e32 v16, 1, v14
	v_and_b32_e32 v16, 24, v16
	v_and_b32_e32 v15, 15, v14
	v_lshlrev_b32_e32 v17, 1, v16
	v_lshlrev_b32_e32 v14, 2, v14
	s_sext_i32_i8 s5, s10
	v_lshl_or_b32 v186, s20, 6, v15
	v_lshl_or_b32 v15, v15, 6, v17
	s_lshl_b32 s10, s20, 13
	v_and_b32_e32 v14, 32, v14
	v_bitop3_b32 v17, v15, s10, v14 bitop3:0xde
	s_lshl_b32 s10, s21, 5
	s_and_b32 s36, s10, 0x60
	s_lshl_b32 s10, s36, 7
	s_add_i32 m0, s19, 0x18000
	v_lshl_add_u64 v[6:7], v[6:7], 0, s[16:17]
	v_bitop3_b32 v187, v15, s10, v14 bitop3:0xde
	global_load_lds_dwordx4 v[6:7], off
	v_lshl_add_u64 v[4:5], v[4:5], 0, s[16:17]
	s_add_i32 m0, s19, 0x1a000
	s_add_i32 s10, s19, 0x8000
	s_add_i32 s67, s19, 0xa000
	global_load_lds_dwordx4 v[4:5], off
	v_lshl_add_u64 v[0:1], v[0:1], 0, s[16:17]
	s_mov_b32 m0, s10
	s_add_u32 s20, s12, 0x40080
	global_load_lds_dwordx4 v[0:1], off
	v_lshl_add_u64 v[0:1], v[2:3], 0, s[16:17]
	s_mov_b32 m0, s67
	s_addc_u32 s21, s13, 0
	global_load_lds_dwordx4 v[0:1], off
	s_add_i32 m0, s19, 0x1c000
	v_lshl_add_u64 v[0:1], s[20:21], 0, v[158:159]
	global_load_lds_dwordx4 v[0:1], off
	v_lshl_add_u64 v[0:1], s[20:21], 0, v[174:175]
	s_add_i32 m0, s19, 0x1e000
	s_cmpk_lt_u32 s3, 0x100
	global_load_lds_dwordx4 v[0:1], off
	v_lshlrev_b32_e32 v0, 14, v11
	v_and_b32_e32 v0, 0xffff8000, v0
	v_lshl_add_u32 v0, v12, 11, v0
	v_and_b32_e32 v1, 1, v11
	v_lshl_or_b32 v0, v1, 6, v0
	v_lshl_add_u32 v176, v13, 1, v0
	v_lshlrev_b32_e32 v0, 14, v8
	v_and_b32_e32 v0, 0xffff8000, v0
	s_waitcnt vmcnt(8)
	s_barrier
	s_waitcnt vmcnt(6)
	v_lshl_add_u32 v0, v9, 11, v0
	v_and_b32_e32 v1, 1, v8
	v_lshl_or_b32 v0, v1, 6, v0
	s_cselect_b64 s[42:43], -1, 0
	v_or_b32_e32 v188, 16, v186
	v_or_b32_e32 v189, 32, v186
	v_or_b32_e32 v190, 48, v186
	v_or_b32_e32 v191, s36, v16
	v_mov_b32_e32 v177, v81
	v_lshl_add_u32 v178, v10, 1, v0
	v_mov_b32_e32 v179, v81
	s_mov_b32 s3, 0
	v_add_u32_e32 v192, 0, v17
	s_barrier
	s_branch .LBB0_433

; #define PG8_STAGE(bufoff, gbase, voff) do { _Pragma("unroll") for (int _i = 0; _i < 2; ++_i) \
;         __builtin_amdgcn_global_load_lds((const unsigned*)((const char*)(gbase) + (voff)[_i]), (PG8_LAS unsigned*)(lds + (bufoff) + ldsw + _i * 8192), 16, 0, 0); } while (0)
; #define PG8_WAIT_V(n) asm volatile("s_waitcnt vmcnt(" #n ")" ::: "memory")
; #define PG8_BAR __builtin_amdgcn_s_barrier()
; template <class Epi, class Sched, bool ALIGN_EPI = false, bool SP2 = false, bool MID = false>
; __device__ __forceinline__ void gemm_phase(PG8_LAS unsigned char* lds, const Gemm g, const Sched& S, const Epi& E, const PG8_LAS float* mid = nullptr) {
;     ...
;     for (int i = 0; i < 2; ++i) { int R, C; stage_rc(tid * 16 + i * 8192, R, C); const int Rb = Epi::PERM ? ((R & ~31) + perm32(R & 31)) : R;
;         voffA[i] = (unsigned)(R * g.lda + C) * 2u; voffB[i] = (unsigned)(Rb * g.ldb + C) * 2u; }
;     const size_t kstep = (size_t)(BK * 2);
;     const size_t hstepA = (size_t)HALF * g.lda * 2, hstepB = (size_t)HALF * g.ldb * 2;
;     const size_t tstepA = 2 * hstepA, tstepB = 2 * hstepB;
;     const unsigned ldsw = (unsigned)wid * 1024u;
;     const int aoff = lds_byte(wr * 64 + fr, fq * 8), boff = lds_byte(wc * 32 + fr, fq * 8);
;     ...
;         PG8_STAGE(PG8_SB(0, 0), cB, voffB); PG8_STAGE(PG8_SB(0, 1), cB + hstepB, voffB); PG8_STAGE(PG8_SA(0, 0), cA, voffA); PG8_STAGE(PG8_SA(0, 1), cA + hstepA, voffA);
;         if (wr == 1) PG8_BAR;
;         PG8_WAIT_V(2); PG8_BAR;
;         PG8_STAGE(PG8_SB(1, 0), cB + kstep, voffB); PG8_STAGE(PG8_SA(1, 0), cA + kstep, voffA); PG8_STAGE(PG8_SB(1, 1), cB + hstepB + kstep, voffB);
;         PG8_WAIT_V(6); PG8_BAR;
.LBB0_553:
	s_add_u32 s79, s36, 0x7400000
	s_addc_u32 s84, s37, 0
	s_add_u32 s94, s36, 0x17400000
	s_addc_u32 s5, s37, 0
	v_bfe_u32 v219, v12, 4, 2
	v_writelane_b32 v255, s5, 43
	v_and_b32_e32 v187, 15, v12
	s_lshl_b32 s5, s40, 6
	v_lshlrev_b32_e32 v15, 4, v219
	v_lshlrev_b32_e32 v12, 2, v12
	v_writelane_b32 v255, s5, 44
	v_lshl_or_b32 v15, v187, 6, v15
	s_lshl_b32 s5, s40, 13
	v_and_b32_e32 v12, 32, v12
	v_bitop3_b32 v16, v15, s5, v12 bitop3:0xde
	s_lshl_b32 s5, s41, 5
	s_and_b32 s5, s5, 0x60
	s_add_i32 m0, s19, 0x18000
	v_lshl_add_u64 v[4:5], v[4:5], 0, s[16:17]
	s_mov_b32 s92, s5
	s_lshl_b32 s5, s5, 7
	global_load_lds_dwordx4 v[4:5], off
	v_lshl_add_u64 v[2:3], v[2:3], 0, s[16:17]
	s_add_i32 m0, s19, 0x1a000
	s_add_i32 s48, s19, 0x8000
	s_add_i32 s49, s19, 0xa000
	global_load_lds_dwordx4 v[2:3], off
	v_lshl_add_u64 v[0:1], v[0:1], 0, s[16:17]
	s_mov_b32 m0, s48
	s_add_u32 s36, s38, 0x40080
	global_load_lds_dwordx4 v[0:1], off
	v_lshl_add_u64 v[0:1], v[6:7], 0, s[16:17]
	s_mov_b32 m0, s49
	s_addc_u32 s37, s39, 0
	global_load_lds_dwordx4 v[0:1], off
	s_add_i32 m0, s19, 0x1c000
	v_lshl_add_u64 v[0:1], s[36:37], 0, v[176:177]
	global_load_lds_dwordx4 v[0:1], off
	v_lshl_add_u64 v[0:1], s[36:37], 0, v[180:181]
	s_add_i32 m0, s19, 0x1e000
	s_cmpk_lt_u32 s3, 0x100
	global_load_lds_dwordx4 v[0:1], off
	s_cselect_b64 s[36:37], -1, 0
	s_ashr_i32 s89, s10, 31
	s_ashr_i32 s3, s82, 31
	s_add_u32 s50, s44, 0x5800
	s_addc_u32 s51, s45, 0
	s_add_u32 s52, s44, 0xb000
	s_addc_u32 s53, s45, 0
	v_lshlrev_b32_e32 v0, 14, v8
	s_add_u32 s54, s44, 0x2c00
	v_and_b32_e32 v0, 0xffff8000, v0
	s_addc_u32 s55, s45, 0
	v_lshl_add_u32 v0, v9, 11, v0
	v_and_b32_e32 v1, 1, v8
	s_add_u32 s56, s44, 0x8400
	v_lshl_or_b32 v0, v1, 6, v0
	s_addc_u32 s57, s45, 0
	v_lshl_add_u32 v182, v10, 1, v0
	v_lshlrev_b32_e32 v0, 14, v11
	s_add_u32 s58, s44, 0xdc00
	v_and_b32_e32 v0, 0xffff8000, v0
	s_waitcnt vmcnt(8)
	s_barrier
	s_waitcnt vmcnt(6)
	v_writelane_b32 v255, s36, 47
	s_addc_u32 s59, s45, 0
	v_lshl_add_u32 v0, v13, 11, v0
	v_and_b32_e32 v1, 1, v11
	v_writelane_b32 v255, s37, 48
	s_add_u32 s60, s14, 0x2c00
	v_lshl_or_b32 v0, v1, 6, v0
	v_bitop3_b32 v220, v15, s5, v12 bitop3:0xde
	v_writelane_b32 v255, s3, 45
	s_addc_u32 s61, s15, 0
	s_lshr_b32 s100, s85, 1
	s_mov_b64 s[98:99], s[44:45]
	s_cmp_eq_u32 s100, 512
	s_cselect_b32 s98, s50, s98
	s_cselect_b32 s99, s51, s99
	s_cmp_eq_u32 s100, 1024
	s_cselect_b32 s98, s52, s98
	s_cselect_b32 s99, s53, s99
	s_cmp_eq_u32 s100, 1536
	s_cselect_b32 s98, s14, s98
	s_cselect_b32 s99, s15, s99
	s_cmp_eq_u32 s100, 2048
	s_cselect_b32 s98, s54, s98
	s_cselect_b32 s99, s55, s99
	s_cmp_eq_u32 s100, 2560
	s_cselect_b32 s98, s56, s98
	s_cselect_b32 s99, s57, s99
	s_cmp_eq_u32 s100, 3072
	s_cselect_b32 s98, s58, s98
	s_cselect_b32 s99, s59, s99
	s_cmp_eq_u32 s100, 3584
	s_cselect_b32 s98, s60, s98
	s_cselect_b32 s99, s61, s99
	s_add_i32 s100, s100, 0x22000
	v_mov_b32_e32 v183, v81
	v_lshl_add_u32 v184, v14, 1, v0
	v_mov_b32_e32 v185, v81
	s_mov_b32 s78, 0
	v_add_u32_e32 v221, 0, v16
	s_barrier
	s_branch .LBB0_556

; #define PG8_STAGE(bufoff, gbase, voff) do { _Pragma("unroll") for (int _i = 0; _i < 2; ++_i) \
;         __builtin_amdgcn_global_load_lds((const unsigned*)((const char*)(gbase) + (voff)[_i]), (PG8_LAS unsigned*)(lds + (bufoff) + ldsw + _i * 8192), 16, 0, 0); } while (0)
; #define PG8_WAIT_V(n) asm volatile("s_waitcnt vmcnt(" #n ")" ::: "memory")
; #define PG8_BAR __builtin_amdgcn_s_barrier()
; template <class Epi, class Sched, bool ALIGN_EPI = false, bool SP2 = false, bool MID = false>
; __device__ __forceinline__ void gemm_phase(PG8_LAS unsigned char* lds, const Gemm g, const Sched& S, const Epi& E, const PG8_LAS float* mid = nullptr) {
;     ...
;     for (int i = 0; i < 2; ++i) { int R, C; stage_rc(tid * 16 + i * 8192, R, C); const int Rb = Epi::PERM ? ((R & ~31) + perm32(R & 31)) : R;
;         voffA[i] = (unsigned)(R * g.lda + C) * 2u; voffB[i] = (unsigned)(Rb * g.ldb + C) * 2u; }
;     const size_t kstep = (size_t)(BK * 2);
;     const size_t hstepA = (size_t)HALF * g.lda * 2, hstepB = (size_t)HALF * g.ldb * 2;
;     const size_t tstepA = 2 * hstepA, tstepB = 2 * hstepB;
;     const unsigned ldsw = (unsigned)wid * 1024u;
;     const int aoff = lds_byte(wr * 64 + fr, fq * 8), boff = lds_byte(wc * 32 + fr, fq * 8);
;     ...
;         PG8_STAGE(PG8_SB(0, 0), cB, voffB); PG8_STAGE(PG8_SB(0, 1), cB + hstepB, voffB); PG8_STAGE(PG8_SA(0, 0), cA, voffA); PG8_STAGE(PG8_SA(0, 1), cA + hstepA, voffA);
;         if (wr == 1) PG8_BAR;
;         PG8_WAIT_V(2); PG8_BAR;
;         PG8_STAGE(PG8_SB(1, 0), cB + kstep, voffB); PG8_STAGE(PG8_SA(1, 0), cA + kstep, voffA); PG8_STAGE(PG8_SB(1, 1), cB + hstepB + kstep, voffB);
;         PG8_WAIT_V(6); PG8_BAR;
.LBB0_691:
	s_add_u32 s40, s20, 0x19000000
	v_lshrrev_b32_e32 v18, 1, v16
	s_addc_u32 s41, s21, 0
	v_and_b32_e32 v18, 24, v18
	s_add_u32 s57, s78, 0x5000
	v_and_b32_e32 v17, 15, v16
	v_lshlrev_b32_e32 v19, 1, v18
	v_lshlrev_b32_e32 v16, 2, v16
	s_addc_u32 s58, s1, 0
	v_lshl_or_b32 v192, s36, 6, v17
	v_lshl_or_b32 v17, v17, 6, v19
	s_lshl_b32 s20, s36, 13
	v_and_b32_e32 v16, 32, v16
	v_bitop3_b32 v19, v17, s20, v16 bitop3:0xde
	s_lshl_b32 s20, s37, 5
	s_and_b32 s36, s20, 0x60
	s_add_i32 m0, s53, 0x18000
	v_lshl_add_u64 v[6:7], v[6:7], 0, s[16:17]
	s_lshl_b32 s20, s36, 7
	global_load_lds_dwordx4 v[6:7], off
	v_lshl_add_u64 v[4:5], v[4:5], 0, s[16:17]
	s_add_i32 m0, s53, 0x1a000
	s_add_i32 s59, s53, 0x8000
	s_add_i32 s60, s53, 0xa000
	v_bitop3_b32 v193, v17, s20, v16 bitop3:0xde
	global_load_lds_dwordx4 v[4:5], off
	v_lshl_add_u64 v[0:1], v[0:1], 0, s[16:17]
	s_mov_b32 m0, s59
	s_add_u32 s20, s12, 0xb0080
	global_load_lds_dwordx4 v[0:1], off
	v_lshl_add_u64 v[0:1], v[2:3], 0, s[16:17]
	s_mov_b32 m0, s60
	s_addc_u32 s21, s13, 0
	global_load_lds_dwordx4 v[0:1], off
	s_add_i32 m0, s53, 0x1c000
	v_lshl_add_u64 v[0:1], s[20:21], 0, v[80:81]
	global_load_lds_dwordx4 v[0:1], off
	v_lshl_add_u64 v[0:1], s[20:21], 0, v[150:151]
	s_add_i32 m0, s53, 0x1e000
	s_cmpk_lt_u32 s3, 0x100
	global_load_lds_dwordx4 v[0:1], off
	s_movk_i32 s3, 0xb00
	v_or_b32_e32 v194, s36, v18
	v_lshrrev_b32_e32 v1, 1, v12
	v_mul_lo_u32 v0, v14, s3
	s_mov_b32 s36, 0xb000
	v_mad_u64_u32 v[0:1], s[20:21], v1, s36, v[0:1]
	v_or_b32_e32 v0, v0, v13
	s_sext_i32_i8 s66, s38
	v_add_lshl_u32 v0, v0, v15, 1
	v_mov_b32_e32 v1, v81
	s_mov_b64 s[38:39], 0xb0080
	v_lshl_add_u64 v[152:153], v[0:1], 0, s[38:39]
	v_lshrrev_b32_e32 v1, 1, v8
	v_mul_lo_u32 v0, v10, s3
	v_mad_u64_u32 v[0:1], s[20:21], v1, s36, v[0:1]
	s_waitcnt vmcnt(8)
	s_barrier
	s_waitcnt vmcnt(6)
	v_or_b32_e32 v0, v0, v9
	v_add_lshl_u32 v0, v0, v11, 1
	v_mov_b32_e32 v1, v81
	s_cselect_b64 s[42:43], -1, 0
	s_ashr_i32 s61, s2, 31
	v_lshl_add_u64 v[154:155], v[0:1], 0, s[38:39]
	s_mov_b32 s62, 0
	v_add_u32_e32 v195, 0, v19
	s_barrier
	s_branch .LBB0_694
